# GEMM K-loops (in-proj, up): LDS-DMA uses SGPR-base addressing, 16 64-bit VALU address adds per iteration removed
# speedup vs baseline: 1.0037x; 1.0037x over previous
.LBB0_138:
	s_add_u32 s6, s0, 0xfff80080
	s_addc_u32 s7, s1, -1
	s_add_i32 s76, 0, 0x10000
	v_add_u32_e32 v0, s76, v149
	ds_read_b128 v[130:133], v0
	ds_read_b128 v[134:137], v0 offset:1024
	ds_read_b128 v[138:141], v0 offset:2048
	ds_read_b128 v[142:145], v0 offset:3072
	s_cmp_eq_u32 s49, 28
	s_cselect_b32 s13, s51, s7
	s_cselect_b32 s12, s50, s6
	s_cselect_b32 s7, s22, s39
	s_cselect_b32 s6, s23, s38
	s_add_i32 m0, s31, 0xc000
	ds_read_b128 v[152:155], v174
	ds_read_b128 v[166:169], v174 offset:1024
	ds_read_b128 v[170:173], v174 offset:2048
	ds_read_b128 v[176:179], v174 offset:3072
	ds_read_b128 v[180:183], v174 offset:4096
	ds_read_b128 v[184:187], v174 offset:5120
	ds_read_b128 v[188:191], v174 offset:6144
	ds_read_b128 v[192:195], v174 offset:7168
	global_load_lds_dwordx4 v162, s[0:1]
	s_add_i32 m0, s31, 0xe000
	s_nop 0
	global_load_lds_dwordx4 v164, s[0:1]
	s_waitcnt lgkmcnt(8)
	s_barrier
	s_waitcnt lgkmcnt(0)
	s_setprio 1
	s_waitcnt lgkmcnt(0)
	v_mfma_f32_16x16x32_bf16 v[126:129], v[130:133], v[152:155], v[126:129]
	v_mfma_f32_16x16x32_bf16 v[122:125], v[138:141], v[152:155], v[122:125]
	v_mfma_f32_16x16x32_bf16 v[114:117], v[130:133], v[170:173], v[114:117]
	v_mfma_f32_16x16x32_bf16 v[106:109], v[138:141], v[170:173], v[106:109]
	v_mfma_f32_16x16x32_bf16 v[98:101], v[130:133], v[180:183], v[98:101]
	v_mfma_f32_16x16x32_bf16 v[90:93], v[138:141], v[180:183], v[90:93]
	v_mfma_f32_16x16x32_bf16 v[82:85], v[130:133], v[188:191], v[82:85]
	v_mfma_f32_16x16x32_bf16 v[74:77], v[138:141], v[188:191], v[74:77]
	v_mfma_f32_16x16x32_bf16 v[126:129], v[134:137], v[166:169], v[126:129]
	v_mfma_f32_16x16x32_bf16 v[122:125], v[142:145], v[166:169], v[122:125]
	v_mfma_f32_16x16x32_bf16 v[114:117], v[134:137], v[176:179], v[114:117]
	v_mfma_f32_16x16x32_bf16 v[106:109], v[142:145], v[176:179], v[106:109]
	v_mfma_f32_16x16x32_bf16 v[98:101], v[134:137], v[184:187], v[98:101]
	v_mfma_f32_16x16x32_bf16 v[90:93], v[142:145], v[184:187], v[90:93]
	v_mfma_f32_16x16x32_bf16 v[82:85], v[134:137], v[192:195], v[82:85]
	v_mfma_f32_16x16x32_bf16 v[74:77], v[142:145], v[192:195], v[74:77]
	s_setprio 0
	s_barrier
	s_add_i32 s78, 0, 0x14000
	s_add_i32 s76, s76, s30
	v_add_u32_e32 v0, s78, v149
	s_mov_b32 m0, s76
	ds_read_b128 v[196:199], v0
	ds_read_b128 v[200:203], v0 offset:1024
	ds_read_b128 v[204:207], v0 offset:2048
	ds_read_b128 v[216:219], v0 offset:3072
	global_load_lds_dwordx4 v158, s[6:7]
	s_add_i32 m0, s76, 0x2000
	s_nop 0
	global_load_lds_dwordx4 v146, s[6:7]
	s_barrier
	s_waitcnt lgkmcnt(0)
	s_setprio 1
	s_waitcnt lgkmcnt(0)
	v_mfma_f32_16x16x32_bf16 v[118:121], v[196:199], v[152:155], v[118:121]
	v_mfma_f32_16x16x32_bf16 v[110:113], v[204:207], v[152:155], v[110:113]
	v_mfma_f32_16x16x32_bf16 v[102:105], v[196:199], v[170:173], v[102:105]
	v_mfma_f32_16x16x32_bf16 v[94:97], v[204:207], v[170:173], v[94:97]
	v_mfma_f32_16x16x32_bf16 v[86:89], v[196:199], v[180:183], v[86:89]
	v_mfma_f32_16x16x32_bf16 v[78:81], v[204:207], v[180:183], v[78:81]
	v_mfma_f32_16x16x32_bf16 v[70:73], v[196:199], v[188:191], v[70:73]
	v_mfma_f32_16x16x32_bf16 v[66:69], v[204:207], v[188:191], v[66:69]
	v_mfma_f32_16x16x32_bf16 v[118:121], v[200:203], v[166:169], v[118:121]
	v_mfma_f32_16x16x32_bf16 v[110:113], v[216:219], v[166:169], v[110:113]
	v_mfma_f32_16x16x32_bf16 v[102:105], v[200:203], v[176:179], v[102:105]
	v_mfma_f32_16x16x32_bf16 v[94:97], v[216:219], v[176:179], v[94:97]
	v_mfma_f32_16x16x32_bf16 v[86:89], v[200:203], v[184:187], v[86:89]
	v_mfma_f32_16x16x32_bf16 v[78:81], v[216:219], v[184:187], v[78:81]
	v_mfma_f32_16x16x32_bf16 v[70:73], v[200:203], v[192:195], v[70:73]
	v_mfma_f32_16x16x32_bf16 v[66:69], v[216:219], v[192:195], v[66:69]
	s_setprio 0
	s_mov_b32 m0, s31
	s_add_u32 s98, s12, 0x80
	s_addc_u32 s99, s13, 0
	s_barrier
	ds_read_b128 v[152:155], v174 offset:16384
	ds_read_b128 v[166:169], v174 offset:17408
	ds_read_b128 v[170:173], v174 offset:18432
	ds_read_b128 v[176:179], v174 offset:19456
	ds_read_b128 v[180:183], v174 offset:20480
	ds_read_b128 v[184:187], v174 offset:21504
	ds_read_b128 v[188:191], v174 offset:22528
	ds_read_b128 v[192:195], v174 offset:23552
	global_load_lds_dwordx4 v160, s[12:13]
	s_mov_b32 m0, s40
	s_nop 0
	global_load_lds_dwordx4 v156, s[12:13]
	s_barrier
	s_waitcnt lgkmcnt(0)
	s_setprio 1
	s_waitcnt lgkmcnt(0)
	v_mfma_f32_16x16x32_bf16 v[62:65], v[130:133], v[152:155], v[62:65]
	v_mfma_f32_16x16x32_bf16 v[58:61], v[138:141], v[152:155], v[58:61]
	v_mfma_f32_16x16x32_bf16 v[50:53], v[130:133], v[170:173], v[50:53]
	v_mfma_f32_16x16x32_bf16 v[42:45], v[138:141], v[170:173], v[42:45]
	v_mfma_f32_16x16x32_bf16 v[34:37], v[130:133], v[180:183], v[34:37]
	v_mfma_f32_16x16x32_bf16 v[26:29], v[138:141], v[180:183], v[26:29]
	v_mfma_f32_16x16x32_bf16 v[18:21], v[130:133], v[188:191], v[18:21]
	v_mfma_f32_16x16x32_bf16 v[10:13], v[138:141], v[188:191], v[10:13]
	v_mfma_f32_16x16x32_bf16 v[62:65], v[134:137], v[166:169], v[62:65]
	v_mfma_f32_16x16x32_bf16 v[58:61], v[142:145], v[166:169], v[58:61]
	v_mfma_f32_16x16x32_bf16 v[50:53], v[134:137], v[176:179], v[50:53]
	v_mfma_f32_16x16x32_bf16 v[42:45], v[142:145], v[176:179], v[42:45]
	v_mfma_f32_16x16x32_bf16 v[34:37], v[134:137], v[184:187], v[34:37]
	v_mfma_f32_16x16x32_bf16 v[26:29], v[142:145], v[184:187], v[26:29]
	v_mfma_f32_16x16x32_bf16 v[18:21], v[134:137], v[192:195], v[18:21]
	v_mfma_f32_16x16x32_bf16 v[10:13], v[142:145], v[192:195], v[10:13]
	s_setprio 0
	s_barrier
	s_add_u32 s76, s6, 0x80000
	s_addc_u32 s77, s7, 0
	s_add_i32 s78, s78, s30
	s_mov_b32 m0, s78
	s_nop 0
	global_load_lds_dwordx4 v158, s[76:77]
	s_add_i32 m0, s78, 0x2000
	s_nop 0
	global_load_lds_dwordx4 v146, s[76:77]
	s_waitcnt vmcnt(6)
	s_barrier
	s_setprio 1
	v_mfma_f32_16x16x32_bf16 v[54:57], v[196:199], v[152:155], v[54:57]
	v_mfma_f32_16x16x32_bf16 v[46:49], v[204:207], v[152:155], v[46:49]
	v_mfma_f32_16x16x32_bf16 v[38:41], v[196:199], v[170:173], v[38:41]
	v_mfma_f32_16x16x32_bf16 v[30:33], v[204:207], v[170:173], v[30:33]
	v_mfma_f32_16x16x32_bf16 v[22:25], v[196:199], v[180:183], v[22:25]
	v_mfma_f32_16x16x32_bf16 v[14:17], v[204:207], v[180:183], v[14:17]
	v_mfma_f32_16x16x32_bf16 v[6:9], v[196:199], v[188:191], v[6:9]
	v_mfma_f32_16x16x32_bf16 v[2:5], v[204:207], v[188:191], v[2:5]
	v_mfma_f32_16x16x32_bf16 v[54:57], v[200:203], v[166:169], v[54:57]
	v_mfma_f32_16x16x32_bf16 v[46:49], v[216:219], v[166:169], v[46:49]
	v_mfma_f32_16x16x32_bf16 v[38:41], v[200:203], v[176:179], v[38:41]
	v_mfma_f32_16x16x32_bf16 v[30:33], v[216:219], v[176:179], v[30:33]
	v_mfma_f32_16x16x32_bf16 v[22:25], v[200:203], v[184:187], v[22:25]
	v_mfma_f32_16x16x32_bf16 v[14:17], v[216:219], v[184:187], v[14:17]
	v_mfma_f32_16x16x32_bf16 v[6:9], v[200:203], v[192:195], v[6:9]
	v_mfma_f32_16x16x32_bf16 v[2:5], v[216:219], v[192:195], v[2:5]
	s_setprio 0
	s_add_i32 s76, 0, 0x18000
	v_add_u32_e32 v0, s76, v149
	s_barrier
	ds_read_b128 v[130:133], v0
	ds_read_b128 v[134:137], v0 offset:1024
	ds_read_b128 v[138:141], v0 offset:2048
	ds_read_b128 v[142:145], v0 offset:3072
	s_add_u32 s12, s12, 0x80000
	s_addc_u32 s13, s13, 0
	s_mov_b32 m0, s41
	ds_read_b128 v[152:155], v174 offset:32768
	ds_read_b128 v[166:169], v174 offset:33792
	ds_read_b128 v[170:173], v174 offset:34816
	ds_read_b128 v[176:179], v174 offset:35840
	ds_read_b128 v[180:183], v174 offset:36864
	ds_read_b128 v[184:187], v174 offset:37888
	ds_read_b128 v[188:191], v174 offset:38912
	ds_read_b128 v[192:195], v174 offset:39936
	global_load_lds_dwordx4 v160, s[12:13]
	s_mov_b32 m0, s60
	s_nop 0
	global_load_lds_dwordx4 v156, s[12:13]
	s_waitcnt lgkmcnt(8)
	s_barrier
	s_waitcnt lgkmcnt(0)
	s_setprio 1
	s_waitcnt lgkmcnt(0)
	v_mfma_f32_16x16x32_bf16 v[126:129], v[130:133], v[152:155], v[126:129]
	v_mfma_f32_16x16x32_bf16 v[122:125], v[138:141], v[152:155], v[122:125]
	v_mfma_f32_16x16x32_bf16 v[114:117], v[130:133], v[170:173], v[114:117]
	v_mfma_f32_16x16x32_bf16 v[106:109], v[138:141], v[170:173], v[106:109]
	v_mfma_f32_16x16x32_bf16 v[98:101], v[130:133], v[180:183], v[98:101]
	v_mfma_f32_16x16x32_bf16 v[90:93], v[138:141], v[180:183], v[90:93]
	v_mfma_f32_16x16x32_bf16 v[82:85], v[130:133], v[188:191], v[82:85]
	v_mfma_f32_16x16x32_bf16 v[74:77], v[138:141], v[188:191], v[74:77]
	v_mfma_f32_16x16x32_bf16 v[126:129], v[134:137], v[166:169], v[126:129]
	v_mfma_f32_16x16x32_bf16 v[122:125], v[142:145], v[166:169], v[122:125]
	v_mfma_f32_16x16x32_bf16 v[114:117], v[134:137], v[176:179], v[114:117]
	v_mfma_f32_16x16x32_bf16 v[106:109], v[142:145], v[176:179], v[106:109]
	v_mfma_f32_16x16x32_bf16 v[98:101], v[134:137], v[184:187], v[98:101]
	v_mfma_f32_16x16x32_bf16 v[90:93], v[142:145], v[184:187], v[90:93]
	v_mfma_f32_16x16x32_bf16 v[82:85], v[134:137], v[192:195], v[82:85]
	v_mfma_f32_16x16x32_bf16 v[74:77], v[142:145], v[192:195], v[74:77]
	s_setprio 0
	s_barrier
	s_add_i32 s12, 0, 0x1c000
	s_add_i32 s13, s76, s30
	v_add_u32_e32 v0, s12, v149
	s_add_u32 s100, s6, 0x80
	s_addc_u32 s101, s7, 0
	s_mov_b32 m0, s13
	ds_read_b128 v[196:199], v0
	ds_read_b128 v[200:203], v0 offset:1024
	ds_read_b128 v[204:207], v0 offset:2048
	ds_read_b128 v[216:219], v0 offset:3072
	global_load_lds_dwordx4 v158, s[100:101]
	s_add_i32 m0, s13, 0x2000
	s_nop 0
	global_load_lds_dwordx4 v146, s[100:101]
	s_barrier
	s_waitcnt lgkmcnt(0)
	s_setprio 1
	s_waitcnt lgkmcnt(0)
	v_mfma_f32_16x16x32_bf16 v[118:121], v[196:199], v[152:155], v[118:121]
	v_mfma_f32_16x16x32_bf16 v[110:113], v[204:207], v[152:155], v[110:113]
	v_mfma_f32_16x16x32_bf16 v[102:105], v[196:199], v[170:173], v[102:105]
	v_mfma_f32_16x16x32_bf16 v[94:97], v[204:207], v[170:173], v[94:97]
	v_mfma_f32_16x16x32_bf16 v[86:89], v[196:199], v[180:183], v[86:89]
	v_mfma_f32_16x16x32_bf16 v[78:81], v[204:207], v[180:183], v[78:81]
	v_mfma_f32_16x16x32_bf16 v[70:73], v[196:199], v[188:191], v[70:73]
	v_mfma_f32_16x16x32_bf16 v[66:69], v[204:207], v[188:191], v[66:69]
	v_mfma_f32_16x16x32_bf16 v[118:121], v[200:203], v[166:169], v[118:121]
	v_mfma_f32_16x16x32_bf16 v[110:113], v[216:219], v[166:169], v[110:113]
	v_mfma_f32_16x16x32_bf16 v[102:105], v[200:203], v[176:179], v[102:105]
	v_mfma_f32_16x16x32_bf16 v[94:97], v[216:219], v[176:179], v[94:97]
	v_mfma_f32_16x16x32_bf16 v[86:89], v[200:203], v[184:187], v[86:89]
	v_mfma_f32_16x16x32_bf16 v[78:81], v[216:219], v[184:187], v[78:81]
	v_mfma_f32_16x16x32_bf16 v[70:73], v[200:203], v[192:195], v[70:73]
	v_mfma_f32_16x16x32_bf16 v[66:69], v[216:219], v[192:195], v[66:69]
	s_setprio 0
	s_mov_b32 m0, s64
	s_barrier
	ds_read_b128 v[152:155], v174 offset:49152
	ds_read_b128 v[166:169], v174 offset:50176
	ds_read_b128 v[170:173], v174 offset:51200
	ds_read_b128 v[176:179], v174 offset:52224
	ds_read_b128 v[180:183], v174 offset:53248
	ds_read_b128 v[184:187], v174 offset:54272
	ds_read_b128 v[188:191], v174 offset:55296
	ds_read_b128 v[192:195], v174 offset:56320
	global_load_lds_dwordx4 v160, s[98:99]
	s_mov_b32 m0, s65
	s_nop 0
	global_load_lds_dwordx4 v156, s[98:99]
	s_barrier
	s_waitcnt lgkmcnt(0)
	s_setprio 1
	s_waitcnt lgkmcnt(0)
	v_mfma_f32_16x16x32_bf16 v[62:65], v[130:133], v[152:155], v[62:65]
	v_mfma_f32_16x16x32_bf16 v[58:61], v[138:141], v[152:155], v[58:61]
	v_mfma_f32_16x16x32_bf16 v[50:53], v[130:133], v[170:173], v[50:53]
	v_mfma_f32_16x16x32_bf16 v[42:45], v[138:141], v[170:173], v[42:45]
	v_mfma_f32_16x16x32_bf16 v[34:37], v[130:133], v[180:183], v[34:37]
	v_mfma_f32_16x16x32_bf16 v[26:29], v[138:141], v[180:183], v[26:29]
	v_mfma_f32_16x16x32_bf16 v[18:21], v[130:133], v[188:191], v[18:21]
	v_mfma_f32_16x16x32_bf16 v[10:13], v[138:141], v[188:191], v[10:13]
	v_mfma_f32_16x16x32_bf16 v[62:65], v[134:137], v[166:169], v[62:65]
	v_mfma_f32_16x16x32_bf16 v[58:61], v[142:145], v[166:169], v[58:61]
	v_mfma_f32_16x16x32_bf16 v[50:53], v[134:137], v[176:179], v[50:53]
	v_mfma_f32_16x16x32_bf16 v[42:45], v[142:145], v[176:179], v[42:45]
	v_mfma_f32_16x16x32_bf16 v[34:37], v[134:137], v[184:187], v[34:37]
	v_mfma_f32_16x16x32_bf16 v[26:29], v[142:145], v[184:187], v[26:29]
	v_mfma_f32_16x16x32_bf16 v[18:21], v[134:137], v[192:195], v[18:21]
	v_mfma_f32_16x16x32_bf16 v[10:13], v[142:145], v[192:195], v[10:13]
	s_setprio 0
	s_barrier
	s_add_u32 s6, s6, 0x80080
	s_addc_u32 s7, s7, 0
	s_add_i32 s12, s12, s30
	s_mov_b32 m0, s12
	s_nop 0
	global_load_lds_dwordx4 v158, s[6:7]
	s_add_i32 m0, s12, 0x2000
	s_nop 0
	global_load_lds_dwordx4 v146, s[6:7]
	s_waitcnt vmcnt(6)
	s_barrier
	s_setprio 1
	v_mfma_f32_16x16x32_bf16 v[54:57], v[196:199], v[152:155], v[54:57]
	v_mfma_f32_16x16x32_bf16 v[46:49], v[204:207], v[152:155], v[46:49]
	v_mfma_f32_16x16x32_bf16 v[38:41], v[196:199], v[170:173], v[38:41]
	v_mfma_f32_16x16x32_bf16 v[30:33], v[204:207], v[170:173], v[30:33]
	v_mfma_f32_16x16x32_bf16 v[22:25], v[196:199], v[180:183], v[22:25]
	v_mfma_f32_16x16x32_bf16 v[14:17], v[204:207], v[180:183], v[14:17]
	v_mfma_f32_16x16x32_bf16 v[6:9], v[196:199], v[188:191], v[6:9]
	v_mfma_f32_16x16x32_bf16 v[2:5], v[204:207], v[188:191], v[2:5]
	v_mfma_f32_16x16x32_bf16 v[54:57], v[200:203], v[166:169], v[54:57]
	v_mfma_f32_16x16x32_bf16 v[46:49], v[216:219], v[166:169], v[46:49]
	v_mfma_f32_16x16x32_bf16 v[38:41], v[200:203], v[176:179], v[38:41]
	v_mfma_f32_16x16x32_bf16 v[30:33], v[216:219], v[176:179], v[30:33]
	v_mfma_f32_16x16x32_bf16 v[22:25], v[200:203], v[184:187], v[22:25]
	v_mfma_f32_16x16x32_bf16 v[14:17], v[216:219], v[184:187], v[14:17]
	v_mfma_f32_16x16x32_bf16 v[6:9], v[200:203], v[192:195], v[6:9]
	v_mfma_f32_16x16x32_bf16 v[2:5], v[216:219], v[192:195], v[2:5]
	s_setprio 0
	s_add_i32 s49, s49, 2
	s_add_u32 s0, s0, 0x100
	s_addc_u32 s1, s1, 0
	s_add_u32 s38, s38, 0x100
	s_addc_u32 s39, s39, 0
	s_cmp_gt_u32 s49, 29
	s_barrier
	s_cbranch_scc0 .LBB0_138
	v_mov_b32_e32 v0, v148
	s_cmp_gt_i32 s69, 15
	v_and_b32_e32 v176, 15, v0
	v_bfe_u32 v175, v0, 4, 2
	s_mov_b64 s[0:1], -1
	s_cbranch_scc0 .LBB0_157
	s_cmp_gt_u32 s69, 23
	s_cbranch_scc0 .LBB0_154
	s_cmp_gt_u32 s69, 31
	s_cbranch_scc0 .LBB0_151
	s_cmp_gt_u32 s69, 39
	s_cbranch_scc0 .LBB0_148
	v_mul_f32_e32 v0, 0xbfb8aa3b, v126
	v_exp_f32_e32 v131, v0
	s_lshr_b32 s0, s75, 3
	s_mulk_i32 s0, 0x880
	s_lshl_b32 s1, s75, 8
	v_add_f32_e32 v131, 1.0, v131
	v_rcp_f32_e32 v132, v131
	v_mul_f32_e32 v131, 0xbfb8aa3b, v122
	v_mul_f32_e32 v133, 0xbfb8aa3b, v127
	v_mul_f32_e32 v134, 0xbfb8aa3b, v123
	v_mul_f32_e32 v135, 0xbfb8aa3b, v128
	v_mul_f32_e32 v136, 0xbfb8aa3b, v124
	v_mul_f32_e32 v137, 0xbfb8aa3b, v129
	v_mul_f32_e32 v138, 0xbfb8aa3b, v125
	v_mul_f32_e32 v139, 0xbfb8aa3b, v118
	v_mul_f32_e32 v140, 0xbfb8aa3b, v110
	v_mul_f32_e32 v141, 0xbfb8aa3b, v119
	v_mul_f32_e32 v142, 0xbfb8aa3b, v111
	v_mul_f32_e32 v143, 0xbfb8aa3b, v120
	v_mul_f32_e32 v152, 0xbfb8aa3b, v112
	v_mul_f32_e32 v153, 0xbfb8aa3b, v121
	v_mul_f32_e32 v154, 0xbfb8aa3b, v113
	v_mul_f32_e32 v155, 0xbfb8aa3b, v114
	v_mul_f32_e32 v177, 0xbfb8aa3b, v106
	v_mul_f32_e32 v178, 0xbfb8aa3b, v115
	v_mul_f32_e32 v179, 0xbfb8aa3b, v107
	v_mul_f32_e32 v180, 0xbfb8aa3b, v116
	v_mul_f32_e32 v181, 0xbfb8aa3b, v108
	v_mul_f32_e32 v182, 0xbfb8aa3b, v117
	v_mul_f32_e32 v183, 0xbfb8aa3b, v109
	v_mul_f32_e32 v184, 0xbfb8aa3b, v102
	v_mul_f32_e32 v185, 0xbfb8aa3b, v94
	v_mul_f32_e32 v186, 0xbfb8aa3b, v103
	v_mul_f32_e32 v187, 0xbfb8aa3b, v95
	v_mul_f32_e32 v188, 0xbfb8aa3b, v104
	v_mul_f32_e32 v189, 0xbfb8aa3b, v96
	v_mul_f32_e32 v190, 0xbfb8aa3b, v105
	v_mul_f32_e32 v191, 0xbfb8aa3b, v97
	v_mul_f32_e32 v192, 0xbfb8aa3b, v98
	v_mul_f32_e32 v193, 0xbfb8aa3b, v90
	v_mul_f32_e32 v194, 0xbfb8aa3b, v99
	v_mul_f32_e32 v195, 0xbfb8aa3b, v91
	v_mul_f32_e32 v196, 0xbfb8aa3b, v100
	v_mul_f32_e32 v197, 0xbfb8aa3b, v92
	v_mul_f32_e32 v198, 0xbfb8aa3b, v101
	v_mul_f32_e32 v199, 0xbfb8aa3b, v93
	v_mul_f32_e32 v200, 0xbfb8aa3b, v86
	v_mul_f32_e32 v201, 0xbfb8aa3b, v78
	v_mul_f32_e32 v202, 0xbfb8aa3b, v87
	v_mul_f32_e32 v203, 0xbfb8aa3b, v79
	v_mul_f32_e32 v204, 0xbfb8aa3b, v88
	v_mul_f32_e32 v205, 0xbfb8aa3b, v80
	v_mul_f32_e32 v206, 0xbfb8aa3b, v89
	v_mul_f32_e32 v207, 0xbfb8aa3b, v81
	v_mul_f32_e32 v208, 0xbfb8aa3b, v82
	v_mul_f32_e32 v209, 0xbfb8aa3b, v74
	v_mul_f32_e32 v215, 0xbfb8aa3b, v83
	v_mul_f32_e32 v216, 0xbfb8aa3b, v75
	v_mul_f32_e32 v217, 0xbfb8aa3b, v84
	v_mul_f32_e32 v218, 0xbfb8aa3b, v76
	v_mul_f32_e32 v219, 0xbfb8aa3b, v85
	v_mul_f32_e32 v220, 0xbfb8aa3b, v77
	v_mul_f32_e32 v221, 0xbfb8aa3b, v70
	v_mul_f32_e32 v222, 0xbfb8aa3b, v66
	v_mul_f32_e32 v223, 0xbfb8aa3b, v71
	v_mul_f32_e32 v224, 0xbfb8aa3b, v67
	v_mul_f32_e32 v225, 0xbfb8aa3b, v72
	v_mul_f32_e32 v226, 0xbfb8aa3b, v68
	v_mul_f32_e32 v227, 0xbfb8aa3b, v73
	v_mul_f32_e32 v228, 0xbfb8aa3b, v69
	v_mul_f32_e32 v229, 0xbfb8aa3b, v62
	v_mul_f32_e32 v230, 0xbfb8aa3b, v58
	v_mul_f32_e32 v231, 0xbfb8aa3b, v63
	v_mul_f32_e32 v232, 0xbfb8aa3b, v59
	v_mul_f32_e32 v233, 0xbfb8aa3b, v64
	v_mul_f32_e32 v234, 0xbfb8aa3b, v60
	v_mul_f32_e32 v235, 0xbfb8aa3b, v65
	v_mul_f32_e32 v236, 0xbfb8aa3b, v61
	v_mul_f32_e32 v237, 0xbfb8aa3b, v54
	v_mul_f32_e32 v238, 0xbfb8aa3b, v46
	v_mul_f32_e32 v239, 0xbfb8aa3b, v55
	s_and_b32 s1, s1, 0x700
	s_add_i32 s0, s0, s66
	v_exp_f32_e32 v173, v131
	v_exp_f32_e32 v133, v133
	v_exp_f32_e32 v172, v134
	v_exp_f32_e32 v171, v135
	v_exp_f32_e32 v170, v136
	v_exp_f32_e32 v169, v137
	v_exp_f32_e32 v131, v138
	v_exp_f32_e32 v168, v139
	v_exp_f32_e32 v167, v140
	v_exp_f32_e32 v166, v141
	v_exp_f32_e32 v145, v142
	v_exp_f32_e32 v144, v143
	v_exp_f32_e32 v143, v152
	v_exp_f32_e32 v142, v153
	v_exp_f32_e32 v141, v154
	v_exp_f32_e32 v140, v155
	v_exp_f32_e32 v139, v177
	v_exp_f32_e32 v138, v178
	v_exp_f32_e32 v213, v179
	v_exp_f32_e32 v155, v180
	v_exp_f32_e32 v154, v181
	v_exp_f32_e32 v153, v182
	v_exp_f32_e32 v152, v183
	v_exp_f32_e32 v212, v184
	v_exp_f32_e32 v211, v185
	v_exp_f32_e32 v252, v186
	v_exp_f32_e32 v251, v187
	v_exp_f32_e32 v250, v188
	v_exp_f32_e32 v249, v189
	v_exp_f32_e32 v248, v190
	v_exp_f32_e32 v247, v191
	v_exp_f32_e32 v246, v192
	v_exp_f32_e32 v245, v193
	v_exp_f32_e32 v244, v194
	v_exp_f32_e32 v243, v195
	v_exp_f32_e32 v242, v196
	v_exp_f32_e32 v241, v197
	v_exp_f32_e32 v184, v198
	v_exp_f32_e32 v177, v199
	v_exp_f32_e32 v198, v200
	v_exp_f32_e32 v199, v201
	v_exp_f32_e32 v197, v202
	v_exp_f32_e32 v196, v203
	v_exp_f32_e32 v195, v204
	v_exp_f32_e32 v194, v205
	v_exp_f32_e32 v193, v206
	v_exp_f32_e32 v192, v207
	v_exp_f32_e32 v191, v208
	v_exp_f32_e32 v190, v209
	v_exp_f32_e32 v189, v215
	v_exp_f32_e32 v188, v216
	v_exp_f32_e32 v187, v217
	v_exp_f32_e32 v186, v218
	v_exp_f32_e32 v185, v219
	v_exp_f32_e32 v201, v220
	v_exp_f32_e32 v200, v221
	v_exp_f32_e32 v221, v222
	v_exp_f32_e32 v220, v223
	v_exp_f32_e32 v219, v224
	v_exp_f32_e32 v218, v225
	v_exp_f32_e32 v217, v226
	v_exp_f32_e32 v216, v227
	v_exp_f32_e32 v215, v228
	v_exp_f32_e32 v209, v229
	v_exp_f32_e32 v208, v230
	v_exp_f32_e32 v207, v231
	v_exp_f32_e32 v206, v232
	v_exp_f32_e32 v205, v233
	v_exp_f32_e32 v204, v234
	v_exp_f32_e32 v203, v235
	v_exp_f32_e32 v202, v236
	v_exp_f32_e32 v223, v237
	v_exp_f32_e32 v222, v238
	v_exp_f32_e32 v238, v239
	s_add_i32 s0, s0, s1
	s_lshl_b32 s1, s69, 8
	v_lshl_or_b32 v130, v175, 3, s1
	s_cmp_gt_u32 s69, 47
	v_or_b32_e32 v240, s0, v176
	v_or_b32_e32 v130, s61, v130
	s_mov_b64 s[0:1], -1
	v_mul_f32_e32 v237, 0xbfb8aa3b, v47
	v_mul_f32_e32 v236, 0xbfb8aa3b, v56
	v_mul_f32_e32 v235, 0xbfb8aa3b, v48
	v_mul_f32_e32 v234, 0xbfb8aa3b, v57
	v_mul_f32_e32 v233, 0xbfb8aa3b, v49
	v_mul_f32_e32 v232, 0xbfb8aa3b, v50
	v_mul_f32_e32 v231, 0xbfb8aa3b, v42
	v_mul_f32_e32 v230, 0xbfb8aa3b, v51
	v_mul_f32_e32 v229, 0xbfb8aa3b, v43
	v_mul_f32_e32 v228, 0xbfb8aa3b, v18
	s_cbranch_scc0 .LBB0_145
	v_add_f32_e32 v178, 1.0, v171
	v_rcp_f32_e32 v179, v178
	v_add_f32_e32 v178, 1.0, v170
	v_add_f32_e32 v134, 1.0, v173
	v_add_f32_e32 v135, 1.0, v133
	v_add_f32_e32 v137, 1.0, v172
	v_rcp_f32_e32 v181, v178
	v_add_f32_e32 v178, 1.0, v169
	v_rcp_f32_e32 v134, v134
	v_rcp_f32_e32 v135, v135
	v_rcp_f32_e32 v137, v137
	v_rcp_f32_e32 v180, v178
	v_add_f32_e32 v178, 1.0, v131
	v_rcp_f32_e32 v182, v178
	v_mov_b32_e32 v0, v240
	v_mov_b32_e32 v136, v130
	v_cvt_pk_bf16_f32 v178, v132, v135
	v_cvt_pk_bf16_f32 v179, v179, v180
	v_cvt_pk_bf16_f32 v180, v134, v137
	v_mov_b64_e32 v[134:135], s[8:9]
	v_ashrrev_i32_e32 v137, 31, v136
	v_cvt_pk_bf16_f32 v181, v181, v182
	v_mad_i64_i32 v[182:183], s[0:1], v0, s47, v[134:135]
	v_lshlrev_b64 v[136:137], 1, v[136:137]
	v_lshl_add_u64 v[182:183], v[182:183], 0, v[136:137]
	global_store_dwordx4 v[182:183], v[178:181], off
	s_nop 1
	v_add_f32_e32 v179, 1.0, v167
	v_add_f32_e32 v178, 1.0, v168
	v_rcp_f32_e32 v180, v179
	v_add_f32_e32 v179, 1.0, v166
	v_add_f32_e32 v181, 1.0, v145
	v_add_f32_e32 v239, 1.0, v144
	v_add_f32_e32 v224, 1.0, v143
	v_add_f32_e32 v225, 1.0, v142
	v_add_f32_e32 v226, 1.0, v141
	v_rcp_f32_e32 v178, v178
	v_rcp_f32_e32 v179, v179
	v_rcp_f32_e32 v181, v181
	v_rcp_f32_e32 v239, v239
	v_rcp_f32_e32 v224, v224
	v_rcp_f32_e32 v225, v225
	v_rcp_f32_e32 v226, v226
	v_cvt_pk_bf16_f32 v178, v178, v179
	v_cvt_pk_bf16_f32 v180, v180, v181
	v_cvt_pk_bf16_f32 v179, v239, v225
	v_cvt_pk_bf16_f32 v181, v224, v226
	global_store_dwordx4 v[182:183], v[178:181], off offset:256
	s_nop 1
	v_add_f32_e32 v179, 1.0, v139
	v_add_f32_e32 v178, 1.0, v140
	v_rcp_f32_e32 v180, v179
	v_add_f32_e32 v179, 1.0, v138
	v_add_f32_e32 v183, 1.0, v155
	v_add_f32_e32 v225, 1.0, v153
	v_rcp_f32_e32 v178, v178
	v_rcp_f32_e32 v179, v179
	v_add_f32_e32 v181, 1.0, v213
	v_rcp_f32_e32 v183, v183
	v_add_f32_e32 v224, 1.0, v154
	v_rcp_f32_e32 v225, v225
	v_add_f32_e32 v226, 1.0, v152
	v_rcp_f32_e32 v181, v181
	v_rcp_f32_e32 v224, v224
	v_rcp_f32_e32 v226, v226
	v_add_u32_e32 v182, 16, v0
	v_cvt_pk_bf16_f32 v178, v178, v179
	v_cvt_pk_bf16_f32 v179, v183, v225
	v_mad_i64_i32 v[182:183], s[0:1], v182, s47, v[134:135]
	v_cvt_pk_bf16_f32 v180, v180, v181
	v_cvt_pk_bf16_f32 v181, v224, v226
	v_lshl_add_u64 v[182:183], v[182:183], 0, v[136:137]
	global_store_dwordx4 v[182:183], v[178:181], off
	s_nop 1
	v_add_f32_e32 v179, 1.0, v211
	v_add_f32_e32 v178, 1.0, v212
	v_rcp_f32_e32 v180, v179
	v_add_f32_e32 v179, 1.0, v252
	v_add_f32_e32 v181, 1.0, v251
	v_add_f32_e32 v224, 1.0, v250
	v_add_f32_e32 v225, 1.0, v249
	v_add_f32_e32 v226, 1.0, v248
	v_add_f32_e32 v239, 1.0, v247
	v_rcp_f32_e32 v178, v178
	v_rcp_f32_e32 v179, v179
	v_rcp_f32_e32 v181, v181
	v_rcp_f32_e32 v224, v224
	v_rcp_f32_e32 v225, v225
	v_rcp_f32_e32 v226, v226
	v_rcp_f32_e32 v239, v239
	v_cvt_pk_bf16_f32 v178, v178, v179
	v_cvt_pk_bf16_f32 v180, v180, v181
	v_cvt_pk_bf16_f32 v179, v224, v226
	v_cvt_pk_bf16_f32 v181, v225, v239
	global_store_dwordx4 v[182:183], v[178:181], off offset:256
	s_nop 1
	v_add_f32_e32 v179, 1.0, v245
	v_add_f32_e32 v178, 1.0, v246
	v_rcp_f32_e32 v180, v179
	v_add_f32_e32 v179, 1.0, v244
	v_add_f32_e32 v183, 1.0, v242
	v_add_f32_e32 v225, 1.0, v184
	v_rcp_f32_e32 v178, v178
	v_rcp_f32_e32 v179, v179
	v_add_f32_e32 v181, 1.0, v243
	v_rcp_f32_e32 v183, v183
	v_add_f32_e32 v224, 1.0, v241
	v_rcp_f32_e32 v225, v225
	v_add_f32_e32 v226, 1.0, v177
	v_rcp_f32_e32 v181, v181
	v_rcp_f32_e32 v224, v224
	v_rcp_f32_e32 v226, v226
	v_add_u32_e32 v182, 32, v0
	v_cvt_pk_bf16_f32 v178, v178, v179
	v_cvt_pk_bf16_f32 v179, v183, v225
	v_mad_i64_i32 v[182:183], s[0:1], v182, s47, v[134:135]
	v_cvt_pk_bf16_f32 v180, v180, v181
	v_cvt_pk_bf16_f32 v181, v224, v226
	v_lshl_add_u64 v[182:183], v[182:183], 0, v[136:137]
	global_store_dwordx4 v[182:183], v[178:181], off
	s_nop 1
	v_add_f32_e32 v179, 1.0, v199
	v_add_f32_e32 v178, 1.0, v198
	v_rcp_f32_e32 v180, v179
	v_add_f32_e32 v179, 1.0, v197
	v_add_f32_e32 v181, 1.0, v196
	v_add_f32_e32 v224, 1.0, v195
	v_add_f32_e32 v225, 1.0, v194
	v_add_f32_e32 v226, 1.0, v193
	v_add_f32_e32 v239, 1.0, v192
	v_rcp_f32_e32 v178, v178
	v_rcp_f32_e32 v179, v179
	v_rcp_f32_e32 v181, v181
	v_rcp_f32_e32 v224, v224
	v_rcp_f32_e32 v225, v225
	v_rcp_f32_e32 v226, v226
	v_rcp_f32_e32 v239, v239
	v_cvt_pk_bf16_f32 v178, v178, v179
	v_cvt_pk_bf16_f32 v180, v180, v181
	v_cvt_pk_bf16_f32 v179, v224, v226
	v_cvt_pk_bf16_f32 v181, v225, v239
	global_store_dwordx4 v[182:183], v[178:181], off offset:256
	s_nop 1
	v_add_f32_e32 v179, 1.0, v190
	v_add_f32_e32 v178, 1.0, v191
	v_rcp_f32_e32 v180, v179
	v_add_f32_e32 v179, 1.0, v189
	v_add_f32_e32 v183, 1.0, v187
	v_add_f32_e32 v225, 1.0, v185
	v_rcp_f32_e32 v178, v178
	v_rcp_f32_e32 v179, v179
	v_add_f32_e32 v181, 1.0, v188
	v_rcp_f32_e32 v183, v183
	v_add_f32_e32 v224, 1.0, v186
	v_rcp_f32_e32 v225, v225
	v_add_f32_e32 v226, 1.0, v201
	v_rcp_f32_e32 v181, v181
	v_rcp_f32_e32 v224, v224
	v_rcp_f32_e32 v226, v226
	v_add_u32_e32 v182, 48, v0
	v_cvt_pk_bf16_f32 v178, v178, v179
	v_cvt_pk_bf16_f32 v179, v183, v225
	v_mad_i64_i32 v[182:183], s[0:1], v182, s47, v[134:135]
	v_cvt_pk_bf16_f32 v180, v180, v181
	v_cvt_pk_bf16_f32 v181, v224, v226
	v_lshl_add_u64 v[182:183], v[182:183], 0, v[136:137]
	global_store_dwordx4 v[182:183], v[178:181], off
	s_nop 1
	v_add_f32_e32 v179, 1.0, v221
	v_add_f32_e32 v178, 1.0, v200
	v_rcp_f32_e32 v180, v179
	v_add_f32_e32 v179, 1.0, v220
	v_add_f32_e32 v181, 1.0, v219
	v_add_f32_e32 v224, 1.0, v218
	v_add_f32_e32 v225, 1.0, v217
	v_add_f32_e32 v226, 1.0, v216
	v_add_f32_e32 v239, 1.0, v215
	v_rcp_f32_e32 v178, v178
	v_rcp_f32_e32 v179, v179
	v_rcp_f32_e32 v181, v181
	v_rcp_f32_e32 v224, v224
	v_rcp_f32_e32 v225, v225
	v_rcp_f32_e32 v226, v226
	v_rcp_f32_e32 v239, v239
	v_cvt_pk_bf16_f32 v178, v178, v179
	v_cvt_pk_bf16_f32 v180, v180, v181
	v_cvt_pk_bf16_f32 v179, v224, v226
	v_cvt_pk_bf16_f32 v181, v225, v239
	global_store_dwordx4 v[182:183], v[178:181], off offset:256
	s_nop 1
	v_add_f32_e32 v179, 1.0, v208
	v_add_f32_e32 v178, 1.0, v209
	v_rcp_f32_e32 v180, v179
	v_add_f32_e32 v179, 1.0, v207
	v_add_f32_e32 v183, 1.0, v205
	v_add_f32_e32 v225, 1.0, v203
	v_rcp_f32_e32 v178, v178
	v_rcp_f32_e32 v179, v179
	v_add_f32_e32 v181, 1.0, v206
	v_rcp_f32_e32 v183, v183
	v_add_f32_e32 v224, 1.0, v204
	v_rcp_f32_e32 v225, v225
	v_add_f32_e32 v226, 1.0, v202
	v_rcp_f32_e32 v181, v181
	v_rcp_f32_e32 v224, v224
	v_rcp_f32_e32 v226, v226
	v_add_u32_e32 v182, 0x80, v0
	v_cvt_pk_bf16_f32 v178, v178, v179
	v_cvt_pk_bf16_f32 v179, v183, v225
	v_mad_i64_i32 v[182:183], s[0:1], v182, s47, v[134:135]
	v_cvt_pk_bf16_f32 v180, v180, v181
	v_cvt_pk_bf16_f32 v181, v224, v226
	v_lshl_add_u64 v[182:183], v[182:183], 0, v[136:137]
	global_store_dwordx4 v[182:183], v[178:181], off
	s_nop 1
	v_add_f32_e32 v179, 1.0, v222
	v_rcp_f32_e32 v180, v179
	v_exp_f32_e32 v179, v237
	v_exp_f32_e32 v224, v236
	v_exp_f32_e32 v226, v234
	v_exp_f32_e32 v239, v233
	v_add_f32_e32 v179, 1.0, v179
	v_rcp_f32_e32 v225, v179
	v_exp_f32_e32 v179, v235
	v_add_f32_e32 v178, 1.0, v223
	v_add_f32_e32 v181, 1.0, v238
	v_add_f32_e32 v224, 1.0, v224
	v_add_f32_e32 v179, 1.0, v179
	v_rcp_f32_e32 v227, v179
	v_add_f32_e32 v179, 1.0, v226
	v_add_f32_e32 v226, 1.0, v239
	v_rcp_f32_e32 v178, v178
	v_rcp_f32_e32 v181, v181
	v_rcp_f32_e32 v224, v224
	v_rcp_f32_e32 v179, v179
	v_rcp_f32_e32 v226, v226
	v_cvt_pk_bf16_f32 v178, v178, v181
	v_cvt_pk_bf16_f32 v180, v180, v225
	v_cvt_pk_bf16_f32 v179, v224, v179
	v_cvt_pk_bf16_f32 v181, v227, v226
	global_store_dwordx4 v[182:183], v[178:181], off offset:256
	s_nop 1
	v_exp_f32_e32 v179, v231
	v_mul_f32_e32 v183, 0xbfb8aa3b, v52
	v_mul_f32_e32 v225, 0xbfb8aa3b, v53
	v_exp_f32_e32 v183, v183
	v_add_f32_e32 v179, 1.0, v179
	v_rcp_f32_e32 v181, v179
	v_exp_f32_e32 v179, v229
	v_exp_f32_e32 v225, v225
	v_mul_f32_e32 v226, 0xbfb8aa3b, v45
	v_exp_f32_e32 v178, v232
	v_add_f32_e32 v179, 1.0, v179
	v_rcp_f32_e32 v224, v179
	v_mul_f32_e32 v179, 0xbfb8aa3b, v44
	v_exp_f32_e32 v179, v179
	v_exp_f32_e32 v180, v230
	v_exp_f32_e32 v226, v226
	v_add_f32_e32 v183, 1.0, v183
	v_add_f32_e32 v179, 1.0, v179
	v_rcp_f32_e32 v227, v179
	v_add_f32_e32 v179, 1.0, v225
	v_add_f32_e32 v178, 1.0, v178
	v_add_f32_e32 v180, 1.0, v180
	v_rcp_f32_e32 v183, v183
	v_rcp_f32_e32 v179, v179
	v_add_f32_e32 v225, 1.0, v226
	v_rcp_f32_e32 v178, v178
	v_rcp_f32_e32 v180, v180
	v_rcp_f32_e32 v225, v225
	v_add_u32_e32 v182, 0x90, v0
	v_cvt_pk_bf16_f32 v179, v183, v179
	v_mad_i64_i32 v[182:183], s[0:1], v182, s47, v[134:135]
	v_cvt_pk_bf16_f32 v178, v178, v180
	v_cvt_pk_bf16_f32 v180, v181, v224
	v_cvt_pk_bf16_f32 v181, v227, v225
	v_lshl_add_u64 v[182:183], v[182:183], 0, v[136:137]
	global_store_dwordx4 v[182:183], v[178:181], off
	s_nop 1
	v_mul_f32_e32 v179, 0xbfb8aa3b, v30
	v_exp_f32_e32 v179, v179
	v_mul_f32_e32 v178, 0xbfb8aa3b, v38
	v_mul_f32_e32 v180, 0xbfb8aa3b, v39
	v_mul_f32_e32 v224, 0xbfb8aa3b, v40
	v_add_f32_e32 v179, 1.0, v179
	v_rcp_f32_e32 v181, v179
	v_mul_f32_e32 v179, 0xbfb8aa3b, v31
	v_exp_f32_e32 v179, v179
	v_mul_f32_e32 v226, 0xbfb8aa3b, v41
	v_mul_f32_e32 v227, 0xbfb8aa3b, v33
	v_exp_f32_e32 v178, v178
	v_add_f32_e32 v179, 1.0, v179
	v_rcp_f32_e32 v225, v179
	v_mul_f32_e32 v179, 0xbfb8aa3b, v32
	v_exp_f32_e32 v179, v179
	v_exp_f32_e32 v180, v180
	v_exp_f32_e32 v224, v224
	v_exp_f32_e32 v226, v226
	v_exp_f32_e32 v227, v227
	v_add_f32_e32 v179, 1.0, v179
	v_add_f32_e32 v178, 1.0, v178
	v_add_f32_e32 v180, 1.0, v180
	v_add_f32_e32 v224, 1.0, v224
	v_rcp_f32_e32 v239, v179
	v_add_f32_e32 v179, 1.0, v226
	v_add_f32_e32 v226, 1.0, v227
	v_rcp_f32_e32 v178, v178
	v_rcp_f32_e32 v180, v180
	v_rcp_f32_e32 v224, v224
	v_rcp_f32_e32 v179, v179
	v_rcp_f32_e32 v226, v226
	v_cvt_pk_bf16_f32 v178, v178, v180
	v_cvt_pk_bf16_f32 v180, v181, v225
	v_cvt_pk_bf16_f32 v179, v224, v179
	v_cvt_pk_bf16_f32 v181, v239, v226
	global_store_dwordx4 v[182:183], v[178:181], off offset:256
	s_nop 1
	v_mul_f32_e32 v179, 0xbfb8aa3b, v26
	v_exp_f32_e32 v179, v179
	v_mul_f32_e32 v183, 0xbfb8aa3b, v36
	v_mul_f32_e32 v225, 0xbfb8aa3b, v37
	v_mul_f32_e32 v178, 0xbfb8aa3b, v34
	v_add_f32_e32 v179, 1.0, v179
	v_rcp_f32_e32 v181, v179
	v_mul_f32_e32 v179, 0xbfb8aa3b, v27
	v_exp_f32_e32 v179, v179
	v_mul_f32_e32 v180, 0xbfb8aa3b, v35
	v_exp_f32_e32 v183, v183
	v_exp_f32_e32 v225, v225
	v_add_f32_e32 v179, 1.0, v179
	v_rcp_f32_e32 v224, v179
	v_mul_f32_e32 v179, 0xbfb8aa3b, v28
	v_exp_f32_e32 v179, v179
	v_mul_f32_e32 v226, 0xbfb8aa3b, v29
	v_exp_f32_e32 v178, v178
	v_exp_f32_e32 v180, v180
	v_exp_f32_e32 v226, v226
	v_add_f32_e32 v179, 1.0, v179
	v_add_f32_e32 v183, 1.0, v183
	v_rcp_f32_e32 v227, v179
	v_add_f32_e32 v179, 1.0, v225
	v_add_f32_e32 v178, 1.0, v178
	v_add_f32_e32 v180, 1.0, v180
	v_rcp_f32_e32 v183, v183
	v_rcp_f32_e32 v179, v179
	v_add_f32_e32 v225, 1.0, v226
	v_rcp_f32_e32 v178, v178
	v_rcp_f32_e32 v180, v180
	v_rcp_f32_e32 v225, v225
	v_add_u32_e32 v182, 0xa0, v0
	v_cvt_pk_bf16_f32 v179, v183, v179
	v_mad_i64_i32 v[182:183], s[0:1], v182, s47, v[134:135]
	v_cvt_pk_bf16_f32 v178, v178, v180
	v_cvt_pk_bf16_f32 v180, v181, v224
	v_cvt_pk_bf16_f32 v181, v227, v225
	v_lshl_add_u64 v[182:183], v[182:183], 0, v[136:137]
	global_store_dwordx4 v[182:183], v[178:181], off
	s_nop 1
	v_mul_f32_e32 v179, 0xbfb8aa3b, v14
	v_exp_f32_e32 v179, v179
	v_mul_f32_e32 v178, 0xbfb8aa3b, v22
	v_mul_f32_e32 v180, 0xbfb8aa3b, v23
	v_mul_f32_e32 v224, 0xbfb8aa3b, v24
	v_add_f32_e32 v179, 1.0, v179
	v_rcp_f32_e32 v181, v179
	v_mul_f32_e32 v179, 0xbfb8aa3b, v15
	v_exp_f32_e32 v179, v179
	v_mul_f32_e32 v226, 0xbfb8aa3b, v25
	v_mul_f32_e32 v227, 0xbfb8aa3b, v17
	v_exp_f32_e32 v178, v178
	v_add_f32_e32 v179, 1.0, v179
	v_rcp_f32_e32 v225, v179
	v_mul_f32_e32 v179, 0xbfb8aa3b, v16
	v_exp_f32_e32 v179, v179
	v_exp_f32_e32 v180, v180
	v_exp_f32_e32 v224, v224
	v_exp_f32_e32 v226, v226
	v_exp_f32_e32 v227, v227
	v_add_f32_e32 v179, 1.0, v179
	v_add_f32_e32 v178, 1.0, v178
	v_add_f32_e32 v180, 1.0, v180
	v_add_f32_e32 v224, 1.0, v224
	v_rcp_f32_e32 v239, v179
	v_add_f32_e32 v179, 1.0, v226
	v_add_f32_e32 v226, 1.0, v227
	v_rcp_f32_e32 v178, v178
	v_rcp_f32_e32 v180, v180
	v_rcp_f32_e32 v224, v224
	v_rcp_f32_e32 v179, v179
	v_rcp_f32_e32 v226, v226
	v_cvt_pk_bf16_f32 v178, v178, v180
	v_cvt_pk_bf16_f32 v180, v181, v225
	v_cvt_pk_bf16_f32 v179, v224, v179
	v_cvt_pk_bf16_f32 v181, v239, v226
	global_store_dwordx4 v[182:183], v[178:181], off offset:256
	s_nop 1
	v_mul_f32_e32 v179, 0xbfb8aa3b, v10
	v_exp_f32_e32 v179, v179
	v_mul_f32_e32 v180, 0xbfb8aa3b, v19
	v_mul_f32_e32 v181, 0xbfb8aa3b, v11
	v_exp_f32_e32 v180, v180
	v_exp_f32_e32 v181, v181
	v_add_f32_e32 v179, 1.0, v179
	v_rcp_f32_e32 v182, v179
	v_add_f32_e32 v179, 1.0, v180
	v_add_f32_e32 v180, 1.0, v181
	v_mul_f32_e32 v181, 0xbfb8aa3b, v20
	v_mul_f32_e32 v183, 0xbfb8aa3b, v12
	v_mul_f32_e32 v224, 0xbfb8aa3b, v21
	v_mul_f32_e32 v225, 0xbfb8aa3b, v13
	v_exp_f32_e32 v178, v228
	v_exp_f32_e32 v181, v181
	v_exp_f32_e32 v183, v183
	v_exp_f32_e32 v224, v224
	v_exp_f32_e32 v225, v225
	v_add_f32_e32 v178, 1.0, v178
	v_add_f32_e32 v181, 1.0, v181
	v_add_f32_e32 v183, 1.0, v183
	v_add_f32_e32 v224, 1.0, v224
	v_add_f32_e32 v225, 1.0, v225
	v_rcp_f32_e32 v178, v178
	v_rcp_f32_e32 v179, v179
	v_rcp_f32_e32 v180, v180
	v_rcp_f32_e32 v181, v181
	v_rcp_f32_e32 v183, v183
	v_rcp_f32_e32 v224, v224
	v_rcp_f32_e32 v225, v225
	v_add_u32_e32 v0, 0xb0, v0
	v_mad_i64_i32 v[134:135], s[0:1], v0, s47, v[134:135]
	v_cvt_pk_bf16_f32 v178, v178, v179
	v_cvt_pk_bf16_f32 v179, v181, v224
	v_cvt_pk_bf16_f32 v180, v182, v180
	v_cvt_pk_bf16_f32 v181, v183, v225
	v_lshl_add_u64 v[182:183], v[134:135], 0, v[136:137]
	global_store_dwordx4 v[182:183], v[178:181], off
	v_mul_f32_e32 v134, 0xbfb8aa3b, v2
	v_exp_f32_e32 v134, v134
	v_mul_f32_e32 v135, 0xbfb8aa3b, v7
	v_mul_f32_e32 v136, 0xbfb8aa3b, v3
	v_exp_f32_e32 v135, v135
	v_exp_f32_e32 v136, v136
	v_add_f32_e32 v134, 1.0, v134
	v_rcp_f32_e32 v137, v134
	v_add_f32_e32 v134, 1.0, v135
	v_add_f32_e32 v135, 1.0, v136
	v_mul_f32_e32 v136, 0xbfb8aa3b, v8
	v_mul_f32_e32 v178, 0xbfb8aa3b, v4
	v_exp_f32_e32 v136, v136
	v_exp_f32_e32 v178, v178
	v_mul_f32_e32 v0, 0xbfb8aa3b, v6
	v_rcp_f32_e32 v179, v135
	v_add_f32_e32 v135, 1.0, v136
	v_add_f32_e32 v136, 1.0, v178
	v_mul_f32_e32 v178, 0xbfb8aa3b, v9
	v_mul_f32_e32 v180, 0xbfb8aa3b, v5
	v_exp_f32_e32 v0, v0
	v_exp_f32_e32 v178, v178
	v_exp_f32_e32 v180, v180
	v_rcp_f32_e32 v181, v136
	v_add_f32_e32 v0, 1.0, v0
	v_add_f32_e32 v136, 1.0, v178
	v_add_f32_e32 v178, 1.0, v180
	v_rcp_f32_e32 v0, v0
	v_rcp_f32_e32 v134, v134
	v_rcp_f32_e32 v135, v135
	v_rcp_f32_e32 v136, v136
	v_rcp_f32_e32 v178, v178
	v_cvt_pk_bf16_f32 v134, v0, v134
	v_cvt_pk_bf16_f32 v135, v135, v136
	v_cvt_pk_bf16_f32 v136, v137, v179
	v_cvt_pk_bf16_f32 v137, v181, v178
	global_store_dwordx4 v[182:183], v[134:137], off offset:256
	s_mov_b64 s[0:1], 0

.LBB0_939:
	s_add_u32 s36, s30, 0xfff80080
	s_addc_u32 s37, s31, -1
	s_add_i32 s69, 0, 0x10000
	v_add_u32_e32 v146, s69, v140
	ds_read_b128 v[142:145], v146
	ds_read_b128 v[152:155], v146 offset:1024
	ds_read_b128 v[156:159], v146 offset:2048
	ds_read_b128 v[160:163], v146 offset:3072
	s_cmp_eq_u32 s68, 28
	s_cselect_b32 s39, s27, s37
	s_cselect_b32 s38, s26, s36
	s_cselect_b32 s37, s23, s67
	s_cselect_b32 s36, s42, s43
	s_add_i32 m0, s41, 0xc000
	ds_read_b128 v[164:167], v141
	ds_read_b128 v[168:171], v141 offset:1024
	ds_read_b128 v[172:175], v141 offset:2048
	ds_read_b128 v[176:179], v141 offset:3072
	ds_read_b128 v[180:183], v141 offset:4096
	ds_read_b128 v[184:187], v141 offset:5120
	ds_read_b128 v[188:191], v141 offset:6144
	ds_read_b128 v[192:195], v141 offset:7168
	global_load_lds_dwordx4 v136, s[30:31]
	s_add_i32 m0, s41, 0xe000
	s_nop 0
	global_load_lds_dwordx4 v138, s[30:31]
	s_waitcnt lgkmcnt(8)
	s_barrier
	s_waitcnt lgkmcnt(0)
	s_setprio 1
	s_waitcnt lgkmcnt(0)
	v_mfma_f32_16x16x32_bf16 v[126:129], v[142:145], v[164:167], v[126:129]
	v_mfma_f32_16x16x32_bf16 v[122:125], v[156:159], v[164:167], v[122:125]
	v_mfma_f32_16x16x32_bf16 v[118:121], v[142:145], v[172:175], v[118:121]
	v_mfma_f32_16x16x32_bf16 v[114:117], v[156:159], v[172:175], v[114:117]
	v_mfma_f32_16x16x32_bf16 v[102:105], v[142:145], v[180:183], v[102:105]
	v_mfma_f32_16x16x32_bf16 v[98:101], v[156:159], v[180:183], v[98:101]
	v_mfma_f32_16x16x32_bf16 v[86:89], v[142:145], v[188:191], v[86:89]
	v_mfma_f32_16x16x32_bf16 v[82:85], v[156:159], v[188:191], v[82:85]
	v_mfma_f32_16x16x32_bf16 v[126:129], v[152:155], v[168:171], v[126:129]
	v_mfma_f32_16x16x32_bf16 v[122:125], v[160:163], v[168:171], v[122:125]
	v_mfma_f32_16x16x32_bf16 v[118:121], v[152:155], v[176:179], v[118:121]
	v_mfma_f32_16x16x32_bf16 v[114:117], v[160:163], v[176:179], v[114:117]
	v_mfma_f32_16x16x32_bf16 v[102:105], v[152:155], v[184:187], v[102:105]
	v_mfma_f32_16x16x32_bf16 v[98:101], v[160:163], v[184:187], v[98:101]
	v_mfma_f32_16x16x32_bf16 v[86:89], v[152:155], v[192:195], v[86:89]
	v_mfma_f32_16x16x32_bf16 v[82:85], v[160:163], v[192:195], v[82:85]
	s_setprio 0
	s_barrier
	s_add_i32 s75, 0, 0x14000
	v_add_u32_e32 v146, s75, v140
	s_add_i32 s69, s69, s40
	ds_read_b128 v[196:199], v146
	ds_read_b128 v[200:203], v146 offset:1024
	ds_read_b128 v[204:207], v146 offset:2048
	ds_read_b128 v[216:219], v146 offset:3072
	s_mov_b32 m0, s69
	s_nop 0
	global_load_lds_dwordx4 v0, s[36:37]
	s_add_i32 m0, s69, 0x2000
	s_nop 0
	global_load_lds_dwordx4 v130, s[36:37]
	s_barrier
	s_waitcnt lgkmcnt(0)
	s_setprio 1
	s_waitcnt lgkmcnt(0)
	v_mfma_f32_16x16x32_bf16 v[110:113], v[196:199], v[164:167], v[110:113]
	v_mfma_f32_16x16x32_bf16 v[106:109], v[204:207], v[164:167], v[106:109]
	v_mfma_f32_16x16x32_bf16 v[94:97], v[196:199], v[172:175], v[94:97]
	v_mfma_f32_16x16x32_bf16 v[90:93], v[204:207], v[172:175], v[90:93]
	v_mfma_f32_16x16x32_bf16 v[78:81], v[196:199], v[180:183], v[78:81]
	v_mfma_f32_16x16x32_bf16 v[74:77], v[204:207], v[180:183], v[74:77]
	v_mfma_f32_16x16x32_bf16 v[70:73], v[196:199], v[188:191], v[70:73]
	v_mfma_f32_16x16x32_bf16 v[66:69], v[204:207], v[188:191], v[66:69]
	v_mfma_f32_16x16x32_bf16 v[110:113], v[200:203], v[168:171], v[110:113]
	v_mfma_f32_16x16x32_bf16 v[106:109], v[216:219], v[168:171], v[106:109]
	v_mfma_f32_16x16x32_bf16 v[94:97], v[200:203], v[176:179], v[94:97]
	v_mfma_f32_16x16x32_bf16 v[90:93], v[216:219], v[176:179], v[90:93]
	v_mfma_f32_16x16x32_bf16 v[78:81], v[200:203], v[184:187], v[78:81]
	v_mfma_f32_16x16x32_bf16 v[74:77], v[216:219], v[184:187], v[74:77]
	v_mfma_f32_16x16x32_bf16 v[70:73], v[200:203], v[192:195], v[70:73]
	v_mfma_f32_16x16x32_bf16 v[66:69], v[216:219], v[192:195], v[66:69]
	s_setprio 0
	s_mov_b32 m0, s41
	s_add_u32 s98, s38, 0x80
	s_addc_u32 s99, s39, 0
	s_barrier
	ds_read_b128 v[164:167], v141 offset:16384
	ds_read_b128 v[168:171], v141 offset:17408
	ds_read_b128 v[172:175], v141 offset:18432
	ds_read_b128 v[176:179], v141 offset:19456
	ds_read_b128 v[180:183], v141 offset:20480
	ds_read_b128 v[184:187], v141 offset:21504
	ds_read_b128 v[188:191], v141 offset:22528
	ds_read_b128 v[192:195], v141 offset:23552
	global_load_lds_dwordx4 v134, s[38:39]
	s_mov_b32 m0, s44
	s_nop 0
	global_load_lds_dwordx4 v132, s[38:39]
	s_barrier
	s_waitcnt lgkmcnt(0)
	s_setprio 1
	s_waitcnt lgkmcnt(0)
	v_mfma_f32_16x16x32_bf16 v[62:65], v[142:145], v[164:167], v[62:65]
	v_mfma_f32_16x16x32_bf16 v[58:61], v[156:159], v[164:167], v[58:61]
	v_mfma_f32_16x16x32_bf16 v[54:57], v[142:145], v[172:175], v[54:57]
	v_mfma_f32_16x16x32_bf16 v[50:53], v[156:159], v[172:175], v[50:53]
	v_mfma_f32_16x16x32_bf16 v[38:41], v[142:145], v[180:183], v[38:41]
	v_mfma_f32_16x16x32_bf16 v[34:37], v[156:159], v[180:183], v[34:37]
	v_mfma_f32_16x16x32_bf16 v[22:25], v[142:145], v[188:191], v[22:25]
	v_mfma_f32_16x16x32_bf16 v[18:21], v[156:159], v[188:191], v[18:21]
	v_mfma_f32_16x16x32_bf16 v[62:65], v[152:155], v[168:171], v[62:65]
	v_mfma_f32_16x16x32_bf16 v[58:61], v[160:163], v[168:171], v[58:61]
	v_mfma_f32_16x16x32_bf16 v[54:57], v[152:155], v[176:179], v[54:57]
	v_mfma_f32_16x16x32_bf16 v[50:53], v[160:163], v[176:179], v[50:53]
	v_mfma_f32_16x16x32_bf16 v[38:41], v[152:155], v[184:187], v[38:41]
	v_mfma_f32_16x16x32_bf16 v[34:37], v[160:163], v[184:187], v[34:37]
	v_mfma_f32_16x16x32_bf16 v[22:25], v[152:155], v[192:195], v[22:25]
	v_mfma_f32_16x16x32_bf16 v[18:21], v[160:163], v[192:195], v[18:21]
	s_setprio 0
	s_barrier
	s_add_u32 s76, s36, 0x80000
	s_addc_u32 s77, s37, 0
	s_add_i32 s69, s75, s40
	s_mov_b32 m0, s69
	s_nop 0
	global_load_lds_dwordx4 v0, s[76:77]
	s_add_i32 m0, s69, 0x2000
	s_nop 0
	global_load_lds_dwordx4 v130, s[76:77]
	s_waitcnt vmcnt(6)
	s_barrier
	s_setprio 1
	v_mfma_f32_16x16x32_bf16 v[46:49], v[196:199], v[164:167], v[46:49]
	v_mfma_f32_16x16x32_bf16 v[42:45], v[204:207], v[164:167], v[42:45]
	v_mfma_f32_16x16x32_bf16 v[30:33], v[196:199], v[172:175], v[30:33]
	v_mfma_f32_16x16x32_bf16 v[26:29], v[204:207], v[172:175], v[26:29]
	v_mfma_f32_16x16x32_bf16 v[14:17], v[196:199], v[180:183], v[14:17]
	v_mfma_f32_16x16x32_bf16 v[10:13], v[204:207], v[180:183], v[10:13]
	v_mfma_f32_16x16x32_bf16 v[6:9], v[196:199], v[188:191], v[6:9]
	v_mfma_f32_16x16x32_bf16 v[2:5], v[204:207], v[188:191], v[2:5]
	v_mfma_f32_16x16x32_bf16 v[46:49], v[200:203], v[168:171], v[46:49]
	v_mfma_f32_16x16x32_bf16 v[42:45], v[216:219], v[168:171], v[42:45]
	v_mfma_f32_16x16x32_bf16 v[30:33], v[200:203], v[176:179], v[30:33]
	v_mfma_f32_16x16x32_bf16 v[26:29], v[216:219], v[176:179], v[26:29]
	v_mfma_f32_16x16x32_bf16 v[14:17], v[200:203], v[184:187], v[14:17]
	v_mfma_f32_16x16x32_bf16 v[10:13], v[216:219], v[184:187], v[10:13]
	v_mfma_f32_16x16x32_bf16 v[6:9], v[200:203], v[192:195], v[6:9]
	v_mfma_f32_16x16x32_bf16 v[2:5], v[216:219], v[192:195], v[2:5]
	s_setprio 0
	s_add_i32 s69, 0, 0x18000
	v_add_u32_e32 v149, s69, v140
	s_barrier
	ds_read_b128 v[142:145], v149
	ds_read_b128 v[152:155], v149 offset:1024
	ds_read_b128 v[156:159], v149 offset:2048
	ds_read_b128 v[160:163], v149 offset:3072
	s_add_u32 s38, s38, 0x80000
	s_addc_u32 s39, s39, 0
	s_mov_b32 m0, s45
	ds_read_b128 v[164:167], v141 offset:32768
	ds_read_b128 v[168:171], v141 offset:33792
	ds_read_b128 v[172:175], v141 offset:34816
	ds_read_b128 v[176:179], v141 offset:35840
	ds_read_b128 v[180:183], v141 offset:36864
	ds_read_b128 v[184:187], v141 offset:37888
	ds_read_b128 v[188:191], v141 offset:38912
	ds_read_b128 v[192:195], v141 offset:39936
	global_load_lds_dwordx4 v134, s[38:39]
	s_mov_b32 m0, s50
	s_nop 0
	global_load_lds_dwordx4 v132, s[38:39]
	s_waitcnt lgkmcnt(8)
	s_barrier
	s_waitcnt lgkmcnt(0)
	s_setprio 1
	s_waitcnt lgkmcnt(0)
	v_mfma_f32_16x16x32_bf16 v[126:129], v[142:145], v[164:167], v[126:129]
	v_mfma_f32_16x16x32_bf16 v[122:125], v[156:159], v[164:167], v[122:125]
	v_mfma_f32_16x16x32_bf16 v[118:121], v[142:145], v[172:175], v[118:121]
	v_mfma_f32_16x16x32_bf16 v[114:117], v[156:159], v[172:175], v[114:117]
	v_mfma_f32_16x16x32_bf16 v[102:105], v[142:145], v[180:183], v[102:105]
	v_mfma_f32_16x16x32_bf16 v[98:101], v[156:159], v[180:183], v[98:101]
	v_mfma_f32_16x16x32_bf16 v[86:89], v[142:145], v[188:191], v[86:89]
	v_mfma_f32_16x16x32_bf16 v[82:85], v[156:159], v[188:191], v[82:85]
	v_mfma_f32_16x16x32_bf16 v[126:129], v[152:155], v[168:171], v[126:129]
	v_mfma_f32_16x16x32_bf16 v[122:125], v[160:163], v[168:171], v[122:125]
	v_mfma_f32_16x16x32_bf16 v[118:121], v[152:155], v[176:179], v[118:121]
	v_mfma_f32_16x16x32_bf16 v[114:117], v[160:163], v[176:179], v[114:117]
	v_mfma_f32_16x16x32_bf16 v[102:105], v[152:155], v[184:187], v[102:105]
	v_mfma_f32_16x16x32_bf16 v[98:101], v[160:163], v[184:187], v[98:101]
	v_mfma_f32_16x16x32_bf16 v[86:89], v[152:155], v[192:195], v[86:89]
	v_mfma_f32_16x16x32_bf16 v[82:85], v[160:163], v[192:195], v[82:85]
	s_setprio 0
	s_barrier
	s_add_i32 s38, 0, 0x1c000
	s_add_i32 s39, s69, s40
	v_add_u32_e32 v149, s38, v140
	s_add_u32 s100, s36, 0x80
	s_addc_u32 s101, s37, 0
	s_mov_b32 m0, s39
	ds_read_b128 v[196:199], v149
	ds_read_b128 v[200:203], v149 offset:1024
	ds_read_b128 v[204:207], v149 offset:2048
	ds_read_b128 v[216:219], v149 offset:3072
	global_load_lds_dwordx4 v0, s[100:101]
	s_add_i32 m0, s39, 0x2000
	s_nop 0
	global_load_lds_dwordx4 v130, s[100:101]
	s_barrier
	s_waitcnt lgkmcnt(0)
	s_setprio 1
	s_waitcnt lgkmcnt(0)
	v_mfma_f32_16x16x32_bf16 v[110:113], v[196:199], v[164:167], v[110:113]
	v_mfma_f32_16x16x32_bf16 v[106:109], v[204:207], v[164:167], v[106:109]
	v_mfma_f32_16x16x32_bf16 v[94:97], v[196:199], v[172:175], v[94:97]
	v_mfma_f32_16x16x32_bf16 v[90:93], v[204:207], v[172:175], v[90:93]
	v_mfma_f32_16x16x32_bf16 v[78:81], v[196:199], v[180:183], v[78:81]
	v_mfma_f32_16x16x32_bf16 v[74:77], v[204:207], v[180:183], v[74:77]
	v_mfma_f32_16x16x32_bf16 v[70:73], v[196:199], v[188:191], v[70:73]
	v_mfma_f32_16x16x32_bf16 v[66:69], v[204:207], v[188:191], v[66:69]
	v_mfma_f32_16x16x32_bf16 v[110:113], v[200:203], v[168:171], v[110:113]
	v_mfma_f32_16x16x32_bf16 v[106:109], v[216:219], v[168:171], v[106:109]
	v_mfma_f32_16x16x32_bf16 v[94:97], v[200:203], v[176:179], v[94:97]
	v_mfma_f32_16x16x32_bf16 v[90:93], v[216:219], v[176:179], v[90:93]
	v_mfma_f32_16x16x32_bf16 v[78:81], v[200:203], v[184:187], v[78:81]
	v_mfma_f32_16x16x32_bf16 v[74:77], v[216:219], v[184:187], v[74:77]
	v_mfma_f32_16x16x32_bf16 v[70:73], v[200:203], v[192:195], v[70:73]
	v_mfma_f32_16x16x32_bf16 v[66:69], v[216:219], v[192:195], v[66:69]
	s_setprio 0
	s_mov_b32 m0, s52
	s_barrier
	ds_read_b128 v[164:167], v141 offset:49152
	ds_read_b128 v[168:171], v141 offset:50176
	ds_read_b128 v[172:175], v141 offset:51200
	ds_read_b128 v[176:179], v141 offset:52224
	ds_read_b128 v[180:183], v141 offset:53248
	ds_read_b128 v[184:187], v141 offset:54272
	ds_read_b128 v[188:191], v141 offset:55296
	ds_read_b128 v[192:195], v141 offset:56320
	global_load_lds_dwordx4 v134, s[98:99]
	s_mov_b32 m0, s53
	s_nop 0
	global_load_lds_dwordx4 v132, s[98:99]
	s_barrier
	s_waitcnt lgkmcnt(0)
	s_setprio 1
	s_waitcnt lgkmcnt(0)
	v_mfma_f32_16x16x32_bf16 v[62:65], v[142:145], v[164:167], v[62:65]
	v_mfma_f32_16x16x32_bf16 v[58:61], v[156:159], v[164:167], v[58:61]
	v_mfma_f32_16x16x32_bf16 v[54:57], v[142:145], v[172:175], v[54:57]
	v_mfma_f32_16x16x32_bf16 v[50:53], v[156:159], v[172:175], v[50:53]
	v_mfma_f32_16x16x32_bf16 v[38:41], v[142:145], v[180:183], v[38:41]
	v_mfma_f32_16x16x32_bf16 v[34:37], v[156:159], v[180:183], v[34:37]
	v_mfma_f32_16x16x32_bf16 v[22:25], v[142:145], v[188:191], v[22:25]
	v_mfma_f32_16x16x32_bf16 v[18:21], v[156:159], v[188:191], v[18:21]
	v_mfma_f32_16x16x32_bf16 v[62:65], v[152:155], v[168:171], v[62:65]
	v_mfma_f32_16x16x32_bf16 v[58:61], v[160:163], v[168:171], v[58:61]
	v_mfma_f32_16x16x32_bf16 v[54:57], v[152:155], v[176:179], v[54:57]
	v_mfma_f32_16x16x32_bf16 v[50:53], v[160:163], v[176:179], v[50:53]
	v_mfma_f32_16x16x32_bf16 v[38:41], v[152:155], v[184:187], v[38:41]
	v_mfma_f32_16x16x32_bf16 v[34:37], v[160:163], v[184:187], v[34:37]
	v_mfma_f32_16x16x32_bf16 v[22:25], v[152:155], v[192:195], v[22:25]
	v_mfma_f32_16x16x32_bf16 v[18:21], v[160:163], v[192:195], v[18:21]
	s_setprio 0
	s_barrier
	s_add_u32 s36, s36, 0x80080
	s_addc_u32 s37, s37, 0
	s_add_i32 s38, s38, s40
	s_mov_b32 m0, s38
	s_nop 0
	global_load_lds_dwordx4 v0, s[36:37]
	s_add_i32 m0, s38, 0x2000
	s_nop 0
	global_load_lds_dwordx4 v130, s[36:37]
	s_waitcnt vmcnt(6)
	s_barrier
	s_setprio 1
	v_mfma_f32_16x16x32_bf16 v[46:49], v[196:199], v[164:167], v[46:49]
	v_mfma_f32_16x16x32_bf16 v[42:45], v[204:207], v[164:167], v[42:45]
	v_mfma_f32_16x16x32_bf16 v[30:33], v[196:199], v[172:175], v[30:33]
	v_mfma_f32_16x16x32_bf16 v[26:29], v[204:207], v[172:175], v[26:29]
	v_mfma_f32_16x16x32_bf16 v[14:17], v[196:199], v[180:183], v[14:17]
	v_mfma_f32_16x16x32_bf16 v[10:13], v[204:207], v[180:183], v[10:13]
	v_mfma_f32_16x16x32_bf16 v[6:9], v[196:199], v[188:191], v[6:9]
	v_mfma_f32_16x16x32_bf16 v[2:5], v[204:207], v[188:191], v[2:5]
	v_mfma_f32_16x16x32_bf16 v[46:49], v[200:203], v[168:171], v[46:49]
	v_mfma_f32_16x16x32_bf16 v[42:45], v[216:219], v[168:171], v[42:45]
	v_mfma_f32_16x16x32_bf16 v[30:33], v[200:203], v[176:179], v[30:33]
	v_mfma_f32_16x16x32_bf16 v[26:29], v[216:219], v[176:179], v[26:29]
	v_mfma_f32_16x16x32_bf16 v[14:17], v[200:203], v[184:187], v[14:17]
	v_mfma_f32_16x16x32_bf16 v[10:13], v[216:219], v[184:187], v[10:13]
	v_mfma_f32_16x16x32_bf16 v[6:9], v[200:203], v[192:195], v[6:9]
	v_mfma_f32_16x16x32_bf16 v[2:5], v[216:219], v[192:195], v[2:5]
	s_setprio 0
	s_add_i32 s68, s68, 2
	s_add_u32 s30, s30, 0x100
	s_addc_u32 s31, s31, 0
	s_add_u32 s43, s43, 0x100
	s_addc_u32 s67, s67, 0
	s_cmp_gt_u32 s68, 29
	s_barrier
	s_cbranch_scc0 .LBB0_939
	s_lshr_b32 s23, s66, 3
	s_mulk_i32 s23, 0x880
	s_lshl_b32 s30, s66, 8
	v_mov_b32_e32 v142, v148
	s_and_b32 s30, s30, 0x700
	s_add_i32 s23, s60, s23
	s_add_i32 s23, s23, s30
	v_and_or_b32 v144, v142, 15, s23
	s_lshl_b32 s23, s65, 8
	v_lshrrev_b32_e32 v142, 1, v142
	v_and_or_b32 v142, v142, 24, s23
	v_or_b32_e32 v142, s51, v142
	v_cvt_pk_bf16_f32 v126, v126, v127
	v_cvt_pk_bf16_f32 v127, v128, v129
	v_cvt_pk_bf16_f32 v128, v122, v123
	v_mov_b64_e32 v[122:123], s[6:7]
	v_ashrrev_i32_e32 v143, 31, v142
	v_cvt_pk_bf16_f32 v70, v70, v71
	v_cvt_pk_bf16_f32 v71, v72, v73
	v_cvt_pk_bf16_f32 v72, v66, v67
	v_add_u32_e32 v66, 0x80, v144
	v_cvt_pk_bf16_f32 v129, v124, v125
	v_mad_i64_i32 v[124:125], s[30:31], v144, s74, v[122:123]
	v_lshlrev_b64 v[142:143], 1, v[142:143]
	v_cvt_pk_bf16_f32 v62, v62, v63
	v_cvt_pk_bf16_f32 v63, v64, v65
	v_cvt_pk_bf16_f32 v64, v58, v59
	v_mad_i64_i32 v[58:59], s[30:31], v66, s74, v[122:123]
	v_lshl_add_u64 v[124:125], v[124:125], 0, v[142:143]
	v_cvt_pk_bf16_f32 v110, v110, v111
	v_cvt_pk_bf16_f32 v111, v112, v113
	v_cvt_pk_bf16_f32 v112, v106, v107
	v_cvt_pk_bf16_f32 v113, v108, v109
	v_lshl_add_u64 v[58:59], v[58:59], 0, v[142:143]
	v_cvt_pk_bf16_f32 v46, v46, v47
	v_cvt_pk_bf16_f32 v47, v48, v49
	v_cvt_pk_bf16_f32 v48, v42, v43
	v_cvt_pk_bf16_f32 v49, v44, v45
	global_store_dwordx4 v[124:125], v[110:113], off offset:256
	global_store_dwordx4 v[58:59], v[46:49], off offset:256
	v_cvt_pk_bf16_f32 v94, v94, v95
	v_add_u32_e32 v110, 16, v144
	v_add_u32_e32 v46, 0x90, v144
	v_mad_i64_i32 v[110:111], s[30:31], v110, s74, v[122:123]
	v_mad_i64_i32 v[46:47], s[30:31], v46, s74, v[122:123]
	v_lshl_add_u64 v[110:111], v[110:111], 0, v[142:143]
	v_cvt_pk_bf16_f32 v95, v96, v97
	v_cvt_pk_bf16_f32 v96, v90, v91
	v_cvt_pk_bf16_f32 v97, v92, v93
	v_lshl_add_u64 v[46:47], v[46:47], 0, v[142:143]
	v_cvt_pk_bf16_f32 v30, v30, v31
	v_cvt_pk_bf16_f32 v31, v32, v33
	v_cvt_pk_bf16_f32 v32, v26, v27
	v_cvt_pk_bf16_f32 v33, v28, v29
	global_store_dwordx4 v[110:111], v[94:97], off offset:256
	global_store_dwordx4 v[46:47], v[30:33], off offset:256
	v_cvt_pk_bf16_f32 v78, v78, v79
	v_add_u32_e32 v94, 32, v144
	v_add_u32_e32 v30, 0xa0, v144
	v_mad_i64_i32 v[94:95], s[30:31], v94, s74, v[122:123]
	v_mad_i64_i32 v[30:31], s[30:31], v30, s74, v[122:123]
	v_lshl_add_u64 v[94:95], v[94:95], 0, v[142:143]
	v_cvt_pk_bf16_f32 v79, v80, v81
	v_cvt_pk_bf16_f32 v80, v74, v75
	v_cvt_pk_bf16_f32 v81, v76, v77
	v_lshl_add_u64 v[30:31], v[30:31], 0, v[142:143]
	v_cvt_pk_bf16_f32 v14, v14, v15
	v_cvt_pk_bf16_f32 v15, v16, v17
	v_cvt_pk_bf16_f32 v16, v10, v11
	v_cvt_pk_bf16_f32 v17, v12, v13
	global_store_dwordx4 v[94:95], v[78:81], off offset:256
	global_store_dwordx4 v[30:31], v[14:17], off offset:256
	v_cvt_pk_bf16_f32 v106, v118, v119
	v_add_u32_e32 v78, 48, v144
	v_add_u32_e32 v14, 0xb0, v144
	v_mad_i64_i32 v[78:79], s[30:31], v78, s74, v[122:123]
	v_mad_i64_i32 v[14:15], s[30:31], v14, s74, v[122:123]
	v_cvt_pk_bf16_f32 v107, v120, v121
	v_cvt_pk_bf16_f32 v108, v114, v115
	v_cvt_pk_bf16_f32 v109, v116, v117
	v_cvt_pk_bf16_f32 v90, v102, v103
	v_cvt_pk_bf16_f32 v91, v104, v105
	v_cvt_pk_bf16_f32 v92, v98, v99
	v_cvt_pk_bf16_f32 v93, v100, v101
	v_cvt_pk_bf16_f32 v74, v86, v87
	v_cvt_pk_bf16_f32 v75, v88, v89
	v_cvt_pk_bf16_f32 v76, v82, v83
	v_cvt_pk_bf16_f32 v77, v84, v85
	v_lshl_add_u64 v[78:79], v[78:79], 0, v[142:143]
	v_cvt_pk_bf16_f32 v73, v68, v69
	v_cvt_pk_bf16_f32 v65, v60, v61
	v_cvt_pk_bf16_f32 v42, v54, v55
	v_cvt_pk_bf16_f32 v43, v56, v57
	v_cvt_pk_bf16_f32 v44, v50, v51
	v_cvt_pk_bf16_f32 v45, v52, v53
	v_cvt_pk_bf16_f32 v26, v38, v39
	v_cvt_pk_bf16_f32 v27, v40, v41
	v_cvt_pk_bf16_f32 v28, v34, v35
	v_cvt_pk_bf16_f32 v29, v36, v37
	v_cvt_pk_bf16_f32 v10, v22, v23
	v_cvt_pk_bf16_f32 v11, v24, v25
	v_cvt_pk_bf16_f32 v12, v18, v19
	v_cvt_pk_bf16_f32 v13, v20, v21
	v_lshl_add_u64 v[14:15], v[14:15], 0, v[142:143]
	v_cvt_pk_bf16_f32 v6, v6, v7
	v_cvt_pk_bf16_f32 v7, v8, v9
	v_cvt_pk_bf16_f32 v8, v2, v3
	v_cvt_pk_bf16_f32 v9, v4, v5
	s_and_b64 vcc, exec, s[0:1]
	s_mov_b32 s65, s22
	s_mov_b32 s66, s64
	s_mov_b64 s[36:37], s[28:29]
	s_mov_b64 s[30:31], s[26:27]
	global_store_dwordx4 v[124:125], v[126:129], off
	global_store_dwordx4 v[110:111], v[106:109], off
	global_store_dwordx4 v[94:95], v[90:93], off
	global_store_dwordx4 v[78:79], v[74:77], off
	global_store_dwordx4 v[78:79], v[70:73], off offset:256
	global_store_dwordx4 v[58:59], v[62:65], off
	global_store_dwordx4 v[46:47], v[42:45], off
	global_store_dwordx4 v[30:31], v[26:29], off
	global_store_dwordx4 v[14:15], v[10:13], off
	global_store_dwordx4 v[14:15], v[6:9], off offset:256
	s_cbranch_vccz .LBB0_934
	s_waitcnt vmcnt(0)
	s_cmpk_gt_u32 s14, 0xff
	s_cbranch_scc1 .LBB0_943
	s_barrier
